# GEMM prologues (5 instances): K-tile 1 staging loads issued together with K-tile 0 (first wait+barrier moved below them, vmcnt 2 -> 8); on top of step-1 LDS-DMA prefetch
# speedup vs baseline: 1.0050x; 1.0050x over previous
; #define PG8_STAGE(bufoff, gbase, voff) do { _Pragma("unroll") for (int _i = 0; _i < 2; ++_i) \
;         __builtin_amdgcn_global_load_lds((const unsigned*)((const char*)(gbase) + (voff)[_i]), (PG8_LAS unsigned*)(lds + (bufoff) + ldsw + _i * 8192), 16, 0, 0); } while (0)
; #define PG8_WAIT_V(n) asm volatile("s_waitcnt vmcnt(" #n ")" ::: "memory")
; #define PG8_BAR __builtin_amdgcn_s_barrier()
; template <class Epi, class Sched, bool ALIGN_EPI = false, bool SP2 = false>
; __device__ __forceinline__ void gemm_phase(PG8_LAS unsigned char* lds, const Gemm g, const Sched& S, const Epi& E) {
;     ...
;         PG8_STAGE(PG8_SB(0, 0), cB, voffB); PG8_STAGE(PG8_SB(0, 1), cB + hstep, voffB); PG8_STAGE(PG8_SA(0, 0), cA, voffA); PG8_STAGE(PG8_SA(0, 1), cA + hstep, voffA);
;         if (wr == 1) PG8_BAR;
;         PG8_WAIT_V(2); PG8_BAR;
;         PG8_STAGE(PG8_SB(1, 0), cB + kstep, voffB); PG8_STAGE(PG8_SA(1, 0), cA + kstep, voffA); PG8_STAGE(PG8_SB(1, 1), cB + hstep + kstep, voffB);
;         PG8_WAIT_V(6); PG8_BAR;
.LBB0_139:
	s_sext_i32_i8 s61, s24
	s_add_u32 s24, s6, 0x6300000
	s_waitcnt vmcnt(0)
	v_lshrrev_b32_e32 v15, 1, v14
	s_addc_u32 s25, s7, 0
	v_and_b32_e32 v15, 24, v15
	s_lshl_b32 s27, s27, 5
	v_and_b32_e32 v33, 15, v14
	v_lshlrev_b32_e32 v16, 1, v15
	v_lshlrev_b32_e32 v14, 2, v14
	s_and_b32 s30, s27, 0x60
	s_add_i32 m0, s52, 0x18000
	v_lshl_add_u64 v[6:7], v[6:7], 0, s[8:9]
	s_lshl_b32 s57, s28, 6
	v_lshl_or_b32 v16, v33, 6, v16
	s_lshl_b32 s28, s28, 13
	v_and_b32_e32 v14, 32, v14
	s_lshl_b32 s27, s30, 7
	global_load_lds_dwordx4 v[6:7], off
	v_lshl_add_u64 v[4:5], v[4:5], 0, s[8:9]
	s_add_i32 m0, s52, 0x1a000
	s_add_i32 s58, s52, 0x8000
	s_add_i32 s59, s52, 0xa000
	v_bitop3_b32 v17, v16, s28, v14 bitop3:0xde
	global_load_lds_dwordx4 v[4:5], off
	v_lshl_add_u64 v[0:1], v[0:1], 0, s[8:9]
	s_mov_b32 m0, s58
	s_add_u32 s28, s50, 0x40080
	global_load_lds_dwordx4 v[0:1], off
	v_lshl_add_u64 v[0:1], v[2:3], 0, s[8:9]
	s_mov_b32 m0, s59
	s_addc_u32 s29, s51, 0
	global_load_lds_dwordx4 v[0:1], off
	s_add_i32 m0, s52, 0x1c000
	v_lshl_add_u64 v[0:1], s[28:29], 0, v[134:135]
	global_load_lds_dwordx4 v[0:1], off
	v_lshl_add_u64 v[0:1], s[28:29], 0, v[130:131]
	s_add_i32 m0, s52, 0x1e000
	s_cmpk_lt_u32 s26, 0x100
	global_load_lds_dwordx4 v[0:1], off
	s_waitcnt vmcnt(8)
	s_barrier
	v_lshlrev_b32_e32 v0, 14, v12
	v_and_b32_e32 v0, 0xffff8000, v0
	v_lshl_add_u32 v0, v11, 11, v0
	v_and_b32_e32 v1, 1, v12
	v_lshl_or_b32 v0, v1, 6, v0
	v_lshl_add_u32 v138, v13, 1, v0
	v_lshlrev_b32_e32 v0, 14, v8
	v_and_b32_e32 v0, 0xffff8000, v0
	s_waitcnt vmcnt(6)
	v_lshl_add_u32 v0, v9, 11, v0
	v_and_b32_e32 v1, 1, v8
	v_lshl_or_b32 v0, v1, 6, v0
	v_bitop3_b32 v145, v16, s27, v14 bitop3:0xde
	s_cselect_b64 s[26:27], -1, 0
	v_or_b32_e32 v148, s30, v15
	v_mov_b32_e32 v139, v32
	v_lshl_add_u32 v140, v10, 1, v0
	v_mov_b32_e32 v141, v32
	s_mov_b32 s60, 0
	v_add_u32_e32 v149, 0, v17
	s_barrier
	s_branch .LBB0_142

; #define PG8_STAGE(bufoff, gbase, voff) do { _Pragma("unroll") for (int _i = 0; _i < 2; ++_i) \
;         __builtin_amdgcn_global_load_lds((const unsigned*)((const char*)(gbase) + (voff)[_i]), (PG8_LAS unsigned*)(lds + (bufoff) + ldsw + _i * 8192), 16, 0, 0); } while (0)
; #define PG8_WAIT_V(n) asm volatile("s_waitcnt vmcnt(" #n ")" ::: "memory")
; #define PG8_BAR __builtin_amdgcn_s_barrier()
;     __device__ __forceinline__ void operator()(const f32x4 (&acc)[2][2][4][2], const Unit& u, int wr, int wc, int fr, int fq) const {
;         const int pn = u.pn, jb = wc * 32 + 8 * fq, rowb = u.pm * BM + wr * 64 + fr;
;         if (pn < 8) {
;             const int h = pn & 3; const bool isK = pn >= 4; bf16_t* dst = isK ? K : Q; const float sc = isK ? 0.0625f : 1.0f;
;             float inv[8];
; #pragma unroll
;             for (int e = 0; e < 8; ++e) inv[e] = __builtin_amdgcn_exp2f(-(float)(jb + e) * (13.287712379549449f / 128.0f));
; template <class Epi, class Sched, bool ALIGN_EPI = false, bool SP2 = false>
; __device__ __forceinline__ void gemm_phase(PG8_LAS unsigned char* lds, const Gemm g, const Sched& S, const Epi& E) {
;     ...
;         PG8_STAGE(PG8_SB(0, 0), cB, voffB); PG8_STAGE(PG8_SB(0, 1), cB + hstep, voffB); PG8_STAGE(PG8_SA(0, 0), cA, voffA); PG8_STAGE(PG8_SA(0, 1), cA + hstep, voffA);
;         if (wr == 1) PG8_BAR;
;         PG8_WAIT_V(2); PG8_BAR;
;         PG8_STAGE(PG8_SB(1, 0), cB + kstep, voffB); PG8_STAGE(PG8_SA(1, 0), cA + kstep, voffA); PG8_STAGE(PG8_SB(1, 1), cB + hstep + kstep, voffB);
;         PG8_WAIT_V(6); PG8_BAR;
.LBB0_543:
	s_add_u32 s26, s6, 0x6300000
	s_addc_u32 s27, s7, 0
	s_add_u32 s28, s6, 0xa300000
	s_addc_u32 s29, s7, 0
	s_lshl_b32 s40, s40, 5
	s_and_b32 s42, s40, 0x60
	s_add_i32 m0, s4, 0x18000
	v_lshl_add_u64 v[6:7], v[6:7], 0, s[8:9]
	s_lshl_b32 s49, s41, 6
	s_lshl_b32 s35, s41, 13
	s_lshl_b32 s43, s42, 7
	global_load_lds_dwordx4 v[6:7], off
	v_lshl_add_u64 v[4:5], v[4:5], 0, s[8:9]
	s_add_i32 m0, s4, 0x1a000
	s_add_i32 s58, s4, 0x8000
	s_add_i32 s59, s4, 0xa000
	global_load_lds_dwordx4 v[4:5], off
	v_lshl_add_u64 v[0:1], v[0:1], 0, s[8:9]
	s_mov_b32 m0, s58
	s_add_u32 s40, s50, 0x40080
	global_load_lds_dwordx4 v[0:1], off
	v_lshl_add_u64 v[0:1], v[2:3], 0, s[8:9]
	s_mov_b32 m0, s59
	s_addc_u32 s41, s51, 0
	global_load_lds_dwordx4 v[0:1], off
	s_add_i32 m0, s4, 0x1c000
	v_lshl_add_u64 v[0:1], s[40:41], 0, v[134:135]
	global_load_lds_dwordx4 v[0:1], off
	v_lshl_add_u64 v[0:1], s[40:41], 0, v[130:131]
	s_add_i32 m0, s4, 0x1e000
	v_and_b32_e32 v33, 15, v11
	global_load_lds_dwordx4 v[0:1], off
	s_waitcnt vmcnt(8)
	s_barrier
	v_lshrrev_b32_e32 v0, 1, v11
	v_and_b32_e32 v0, 24, v0
	v_or_b32_e32 v151, s42, v0
	v_lshlrev_b32_e32 v1, 1, v0
	v_cvt_f32_ubyte0_e32 v0, v151
	v_mul_f32_e32 v0, 0xbdd49a78, v0
	v_exp_f32_e32 v153, v0
	v_or_b32_e32 v0, 1, v151
	v_cvt_f32_ubyte0_e32 v0, v0
	v_mul_f32_e32 v0, 0xbdd49a78, v0
	v_exp_f32_e32 v154, v0
	v_or_b32_e32 v0, 2, v151
	v_cvt_f32_ubyte0_e32 v0, v0
	v_mul_f32_e32 v0, 0xbdd49a78, v0
	v_exp_f32_e32 v155, v0
	v_or_b32_e32 v0, 3, v151
	v_cvt_f32_ubyte0_e32 v0, v0
	v_mul_f32_e32 v0, 0xbdd49a78, v0
	v_exp_f32_e32 v156, v0
	v_or_b32_e32 v0, 4, v151
	v_cvt_f32_ubyte0_e32 v0, v0
	v_mul_f32_e32 v0, 0xbdd49a78, v0
	v_exp_f32_e32 v157, v0
	v_or_b32_e32 v0, 5, v151
	v_cvt_f32_ubyte0_e32 v0, v0
	v_mul_f32_e32 v0, 0xbdd49a78, v0
	v_exp_f32_e32 v158, v0
	v_or_b32_e32 v0, 6, v151
	v_cvt_f32_ubyte0_e32 v0, v0
	v_mul_f32_e32 v0, 0xbdd49a78, v0
	v_exp_f32_e32 v159, v0
	v_or_b32_e32 v0, 7, v151
	v_lshlrev_b32_e32 v2, 2, v11
	v_cvt_f32_ubyte0_e32 v0, v0
	v_lshl_or_b32 v1, v33, 6, v1
	v_and_b32_e32 v2, 32, v2
	v_mul_f32_e32 v0, 0xbdd49a78, v0
	v_bitop3_b32 v3, v1, s35, v2 bitop3:0xde
	v_bitop3_b32 v150, v1, s43, v2 bitop3:0xde
	v_exp_f32_e32 v160, v0
	v_lshlrev_b32_e32 v0, 1, v151
	v_mov_b32_e32 v1, v32
	v_lshl_add_u64 v[138:139], s[6:7], 0, v[0:1]
	v_lshlrev_b32_e32 v0, 14, v13
	v_and_b32_e32 v0, 0xffff8000, v0
	v_lshl_add_u32 v0, v12, 11, v0
	v_and_b32_e32 v1, 1, v13
	v_lshl_or_b32 v0, v1, 6, v0
	v_lshl_add_u32 v140, v14, 1, v0
	v_lshlrev_b32_e32 v0, 14, v8
	v_and_b32_e32 v0, 0xffff8000, v0
	s_waitcnt vmcnt(6)
	v_lshl_add_u32 v0, v9, 11, v0
	v_and_b32_e32 v1, 1, v8
	s_cmpk_lt_u32 s31, 0x100
	v_lshl_or_b32 v0, v1, 6, v0
	s_sext_i32_i16 s61, s30
	s_cselect_b64 s[30:31], -1, 0
	v_or_b32_e32 v152, 0xfffff000, v151
	v_mov_b32_e32 v141, v32
	v_lshl_add_u32 v142, v10, 1, v0
	v_mov_b32_e32 v143, v32
	s_mov_b32 s60, 0
	v_add_u32_e32 v161, 0, v3
	s_barrier
	s_branch .LBB0_546

; #define PG8_STAGE(bufoff, gbase, voff) do { _Pragma("unroll") for (int _i = 0; _i < 2; ++_i) \
;         __builtin_amdgcn_global_load_lds((const unsigned*)((const char*)(gbase) + (voff)[_i]), (PG8_LAS unsigned*)(lds + (bufoff) + ldsw + _i * 8192), 16, 0, 0); } while (0)
; #define PG8_WAIT_V(n) asm volatile("s_waitcnt vmcnt(" #n ")" ::: "memory")
; #define PG8_BAR __builtin_amdgcn_s_barrier()
; template <class Epi, class Sched, bool ALIGN_EPI = false, bool SP2 = false>
; __device__ __forceinline__ void gemm_phase(PG8_LAS unsigned char* lds, const Gemm g, const Sched& S, const Epi& E) {
;     ...
;     for (int a = 0; a < 2; ++a)
; #pragma unroll
;         for (int b = 0; b < 2; ++b)
; #pragma unroll
;             for (int m = 0; m < 4; ++m)
; #pragma unroll
;                 for (int n = 0; n < 2; ++n) acc[a][b][m][n] = (f32x4){0.f, 0.f, 0.f, 0.f};
;     bf16x8 At[4][2], B0[2][2], B1[2][2];
;     const char* cA = (const char*)g.A + (size_t)cur.pm * tstep; const char* cB = (const char*)g.Bt + (size_t)cur.pn * tstep;
;     S.a_ready(cur);
;     if constexpr (SP2) {
;         PG8_STAGE(PG8_SB(0, 0), cB, voffB); PG8_STAGE(PG8_SB(0, 1), cB + hstep, voffB); PG8_STAGE(PG8_SA(0, 0), cA, voffA); PG8_STAGE(PG8_SA(0, 1), cA + hstep, voffA);
;         if (wr == 1) PG8_BAR;
;         PG8_WAIT_V(2); PG8_BAR;
;         PG8_STAGE(PG8_SB(1, 0), cB + kstep, voffB); PG8_STAGE(PG8_SA(1, 0), cA + kstep, voffA); PG8_STAGE(PG8_SB(1, 1), cB + hstep + kstep, voffB);
;         PG8_WAIT_V(6); PG8_BAR;
.LBB0_817:
	v_mov_b32_e32 v93, v32
	v_lshl_add_u64 v[6:7], s[6:7], 0, v[92:93]
	v_mov_b32_e32 v95, v32
	v_lshl_add_u64 v[8:9], s[6:7], 0, v[94:95]
	s_add_i32 m0, s19, 0x18000
	v_lshl_add_u64 v[6:7], v[6:7], 0, s[8:9]
	v_lshl_add_u64 v[14:15], s[30:31], 0, v[92:93]
	global_load_lds_dwordx4 v[6:7], off
	v_lshl_add_u64 v[6:7], v[8:9], 0, s[8:9]
	s_add_i32 m0, s19, 0x1a000
	s_add_i32 s60, s19, 0x8000
	v_lshl_add_u64 v[16:17], s[30:31], 0, v[94:95]
	global_load_lds_dwordx4 v[6:7], off
	v_lshl_add_u64 v[6:7], v[14:15], 0, s[8:9]
	s_mov_b32 m0, s60
	s_add_i32 s61, s19, 0xa000
	v_lshl_add_u64 v[10:11], s[36:37], 0, v[92:93]
	global_load_lds_dwordx4 v[6:7], off
	v_lshl_add_u64 v[6:7], v[16:17], 0, s[8:9]
	s_mov_b32 m0, s61
	v_lshl_add_u64 v[12:13], s[36:37], 0, v[94:95]
	global_load_lds_dwordx4 v[6:7], off
	s_add_i32 m0, s19, 0x1c000
	v_lshl_add_u64 v[6:7], v[10:11], 0, s[8:9]
	global_load_lds_dwordx4 v[6:7], off
	v_lshl_add_u64 v[6:7], v[12:13], 0, s[8:9]
	s_add_i32 m0, s19, 0x1e000
	s_sext_i32_i8 s24, s34
	global_load_lds_dwordx4 v[6:7], off
	s_waitcnt vmcnt(8)
	s_barrier
	v_and_b32_e32 v6, 15, v195
	v_lshl_or_b32 v237, s35, 6, v6
	v_and_b32_e32 v7, 48, v195
	v_lshlrev_b32_e32 v192, 6, v237
	s_movk_i32 s34, 0x3c0
	v_lshlrev_b32_e32 v9, 2, v195
	s_and_b32 s25, s44, 3
	s_lshr_b32 s62, s40, 6
	v_and_or_b32 v8, v192, s34, v7
	s_lshl_b32 s34, s35, 13
	v_and_b32_e32 v9, 32, v9
	v_bitop3_b32 v8, v8, s34, v9 bitop3:0xde
	v_lshl_or_b32 v6, v6, 6, v7
	s_lshl_b32 s34, s25, 12
	s_add_i32 s63, s62, -2
	v_bitop3_b32 v106, v6, s34, v9 bitop3:0xde
	s_add_u32 s34, s17, 0x80
	v_add_u32_e32 v0, v2, v0
	s_addc_u32 s35, 0, 0
	v_add_lshl_u32 v0, v0, v1, 1
	v_mov_b32_e32 v1, v32
	v_lshl_add_u64 v[100:101], s[34:35], 0, v[0:1]
	v_add_u32_e32 v0, v5, v3
	s_waitcnt vmcnt(6)
	v_add_lshl_u32 v0, v0, v4, 1
	v_mov_b32_e32 v33, v32
	v_mov_b32_e32 v34, v32
	v_mov_b32_e32 v35, v32
	v_lshl_add_u64 v[102:103], s[34:35], 0, v[0:1]
	v_add_u32_e32 v107, 0, v8
	v_mov_b64_e32 v[0:1], v[32:33]
	v_mov_b64_e32 v[4:5], v[32:33]
	v_mov_b64_e32 v[16:17], v[32:33]
	v_mov_b64_e32 v[20:21], v[32:33]
	v_mov_b64_e32 v[38:39], v[34:35]
	v_mov_b64_e32 v[42:43], v[34:35]
	v_mov_b64_e32 v[54:55], v[34:35]
	v_mov_b64_e32 v[58:59], v[34:35]
	v_mov_b64_e32 v[8:9], v[32:33]
	v_mov_b64_e32 v[12:13], v[32:33]
	v_mov_b64_e32 v[24:25], v[32:33]
	v_mov_b64_e32 v[28:29], v[32:33]
	v_mov_b64_e32 v[46:47], v[34:35]
	v_mov_b64_e32 v[50:51], v[34:35]
	v_mov_b64_e32 v[62:63], v[34:35]
	v_mov_b64_e32 v[66:67], v[34:35]
	v_mov_b64_e32 v[70:71], v[34:35]
	v_mov_b64_e32 v[74:75], v[34:35]
	v_mov_b64_e32 v[86:87], v[34:35]
	v_mov_b64_e32 v[90:91], v[34:35]
	v_mov_b64_e32 v[114:115], v[34:35]
	v_mov_b64_e32 v[122:123], v[34:35]
	v_mov_b64_e32 v[134:135], v[34:35]
	v_mov_b64_e32 v[138:139], v[34:35]
	v_mov_b64_e32 v[78:79], v[34:35]
	v_mov_b64_e32 v[82:83], v[34:35]
	v_mov_b64_e32 v[98:99], v[34:35]
	v_mov_b64_e32 v[110:111], v[34:35]
	v_mov_b64_e32 v[126:127], v[34:35]
	v_mov_b64_e32 v[130:131], v[34:35]
	v_mov_b64_e32 v[142:143], v[34:35]
	v_mov_b64_e32 v[146:147], v[34:35]
	s_mov_b32 s64, 0
	v_mov_b64_e32 v[2:3], v[34:35]
	v_mov_b64_e32 v[6:7], v[34:35]
	v_mov_b64_e32 v[18:19], v[34:35]
	v_mov_b64_e32 v[22:23], v[34:35]
	v_mov_b64_e32 v[36:37], v[32:33]
	v_mov_b64_e32 v[40:41], v[32:33]
	v_mov_b64_e32 v[52:53], v[32:33]
	v_mov_b64_e32 v[56:57], v[32:33]
	v_mov_b64_e32 v[10:11], v[34:35]
	v_mov_b64_e32 v[14:15], v[34:35]
	v_mov_b64_e32 v[26:27], v[34:35]
	v_mov_b64_e32 v[30:31], v[34:35]
	v_mov_b64_e32 v[44:45], v[32:33]
	v_mov_b64_e32 v[48:49], v[32:33]
	v_mov_b64_e32 v[60:61], v[32:33]
	v_mov_b64_e32 v[64:65], v[32:33]
	v_mov_b64_e32 v[68:69], v[32:33]
	v_mov_b64_e32 v[72:73], v[32:33]
	v_mov_b64_e32 v[84:85], v[32:33]
	v_mov_b64_e32 v[88:89], v[32:33]
	v_mov_b64_e32 v[112:113], v[32:33]
	v_mov_b64_e32 v[120:121], v[32:33]
	v_mov_b64_e32 v[132:133], v[32:33]
	v_mov_b64_e32 v[136:137], v[32:33]
	v_mov_b64_e32 v[76:77], v[32:33]
	v_mov_b64_e32 v[80:81], v[32:33]
	v_mov_b64_e32 v[96:97], v[32:33]
	v_mov_b64_e32 v[108:109], v[32:33]
	v_mov_b64_e32 v[124:125], v[32:33]
	v_mov_b64_e32 v[128:129], v[32:33]
	v_mov_b64_e32 v[140:141], v[32:33]
	v_mov_b64_e32 v[144:145], v[32:33]
	s_barrier
	s_branch .LBB0_819

; #define PG8_STAGE(bufoff, gbase, voff) do { _Pragma("unroll") for (int _i = 0; _i < 2; ++_i) \
;         __builtin_amdgcn_global_load_lds((const unsigned*)((const char*)(gbase) + (voff)[_i]), (PG8_LAS unsigned*)(lds + (bufoff) + ldsw + _i * 8192), 16, 0, 0); } while (0)
; #define PG8_WAIT_V(n) asm volatile("s_waitcnt vmcnt(" #n ")" ::: "memory")
; #define PG8_BAR __builtin_amdgcn_s_barrier()
; template <class Epi, class Sched, bool ALIGN_EPI = false, bool SP2 = false>
; __device__ __forceinline__ void gemm_phase(PG8_LAS unsigned char* lds, const Gemm g, const Sched& S, const Epi& E) {
;     ...
;         PG8_STAGE(PG8_SB(0, 0), cB, voffB); PG8_STAGE(PG8_SB(0, 1), cB + hstep, voffB); PG8_STAGE(PG8_SA(0, 0), cA, voffA); PG8_STAGE(PG8_SA(0, 1), cA + hstep, voffA);
;         if (wr == 1) PG8_BAR;
;         PG8_WAIT_V(2); PG8_BAR;
;         PG8_STAGE(PG8_SB(1, 0), cB + kstep, voffB); PG8_STAGE(PG8_SA(1, 0), cA + kstep, voffA); PG8_STAGE(PG8_SB(1, 1), cB + hstep + kstep, voffB);
;         PG8_WAIT_V(6); PG8_BAR;
.LBB0_930:
	v_lshrrev_b32_e32 v16, 1, v14
	v_and_b32_e32 v16, 24, v16
	s_add_u32 s20, s20, 0x4300000
	v_and_b32_e32 v15, 15, v14
	v_lshlrev_b32_e32 v17, 1, v16
	v_lshlrev_b32_e32 v14, 2, v14
	s_sext_i32_i16 s35, s22
	s_addc_u32 s21, s21, 0
	v_lshl_or_b32 v33, s25, 6, v15
	v_lshl_or_b32 v15, v15, 6, v17
	s_lshl_b32 s22, s25, 13
	v_and_b32_e32 v14, 32, v14
	v_bitop3_b32 v17, v15, s22, v14 bitop3:0xde
	s_lshl_b32 s22, s24, 5
	s_and_b32 s26, s22, 0x60
	s_add_i32 m0, s51, 0x18000
	v_lshl_add_u64 v[6:7], v[6:7], 0, s[8:9]
	s_lshl_b32 s22, s26, 7
	global_load_lds_dwordx4 v[6:7], off
	v_lshl_add_u64 v[4:5], v[4:5], 0, s[8:9]
	s_add_i32 m0, s51, 0x1a000
	s_add_i32 s56, s51, 0x8000
	s_add_i32 s57, s51, 0xa000
	global_load_lds_dwordx4 v[4:5], off
	v_lshl_add_u64 v[0:1], v[0:1], 0, s[8:9]
	s_mov_b32 m0, s56
	s_add_u32 s24, s42, 0x40080
	global_load_lds_dwordx4 v[0:1], off
	v_lshl_add_u64 v[0:1], v[2:3], 0, s[8:9]
	s_mov_b32 m0, s57
	s_addc_u32 s25, s43, 0
	global_load_lds_dwordx4 v[0:1], off
	s_add_i32 m0, s51, 0x1c000
	v_lshl_add_u64 v[0:1], s[24:25], 0, v[134:135]
	global_load_lds_dwordx4 v[0:1], off
	v_lshl_add_u64 v[0:1], s[24:25], 0, v[130:131]
	s_add_i32 m0, s51, 0x1e000
	s_cmpk_lt_u32 s23, 0x100
	global_load_lds_dwordx4 v[0:1], off
	s_waitcnt vmcnt(8)
	s_barrier
	v_lshlrev_b32_e32 v0, 14, v12
	v_and_b32_e32 v0, 0xffff8000, v0
	v_lshl_add_u32 v0, v11, 11, v0
	v_and_b32_e32 v1, 1, v12
	v_lshl_or_b32 v0, v1, 6, v0
	v_lshl_add_u32 v138, v13, 1, v0
	v_lshlrev_b32_e32 v0, 14, v8
	v_and_b32_e32 v0, 0xffff8000, v0
	s_waitcnt vmcnt(6)
	v_lshl_add_u32 v0, v9, 11, v0
	v_and_b32_e32 v1, 1, v8
	v_lshl_or_b32 v0, v1, 6, v0
	v_bitop3_b32 v142, v15, s22, v14 bitop3:0xde
	s_cselect_b64 s[22:23], -1, 0
	v_or_b32_e32 v143, s26, v16
	v_mov_b32_e32 v139, v32
	v_lshl_add_u32 v140, v10, 1, v0
	v_mov_b32_e32 v141, v32
	s_mov_b32 s58, 0
	v_add_u32_e32 v144, 0, v17
	s_barrier
	s_branch .LBB0_933

; #define PG8_STAGE(bufoff, gbase, voff) do { _Pragma("unroll") for (int _i = 0; _i < 2; ++_i) \
;         __builtin_amdgcn_global_load_lds((const unsigned*)((const char*)(gbase) + (voff)[_i]), (PG8_LAS unsigned*)(lds + (bufoff) + ldsw + _i * 8192), 16, 0, 0); } while (0)
; #define PG8_WAIT_V(n) asm volatile("s_waitcnt vmcnt(" #n ")" ::: "memory")
; #define PG8_BAR __builtin_amdgcn_s_barrier()
; template <class Epi, class Sched, bool ALIGN_EPI = false, bool SP2 = false>
; __device__ __forceinline__ void gemm_phase(PG8_LAS unsigned char* lds, const Gemm g, const Sched& S, const Epi& E) {
;     ...
;     for (int a = 0; a < 2; ++a)
; #pragma unroll
;         for (int b = 0; b < 2; ++b)
; #pragma unroll
;             for (int m = 0; m < 4; ++m)
; #pragma unroll
;                 for (int n = 0; n < 2; ++n) acc[a][b][m][n] = (f32x4){0.f, 0.f, 0.f, 0.f};
;     bf16x8 At[4][2], B0[2][2], B1[2][2];
;     const char* cA = (const char*)g.A + (size_t)cur.pm * tstep; const char* cB = (const char*)g.Bt + (size_t)cur.pn * tstep;
;     S.a_ready(cur);
;     if constexpr (SP2) {
;         PG8_STAGE(PG8_SB(0, 0), cB, voffB); PG8_STAGE(PG8_SB(0, 1), cB + hstep, voffB); PG8_STAGE(PG8_SA(0, 0), cA, voffA); PG8_STAGE(PG8_SA(0, 1), cA + hstep, voffA);
;         if (wr == 1) PG8_BAR;
;         PG8_WAIT_V(2); PG8_BAR;
;         PG8_STAGE(PG8_SB(1, 0), cB + kstep, voffB); PG8_STAGE(PG8_SA(1, 0), cA + kstep, voffA); PG8_STAGE(PG8_SB(1, 1), cB + hstep + kstep, voffB);
;         PG8_WAIT_V(6); PG8_BAR;
;     } else {
;         PG8_STAGE(PG8_SB(0, 0), cB, voffB); PG8_STAGE(PG8_SA(0, 0), cA, voffA); PG8_STAGE(PG8_SB(0, 1), cB + hstep, voffB); PG8_STAGE(PG8_SA(0, 1), cA + hstep, voffA);
;         if (wr == 1) PG8_BAR;
;         PG8_WAIT_V(4); PG8_BAR;
;         PG8_STAGE(PG8_SB(1, 0), cB + kstep, voffB); PG8_STAGE(PG8_SA(1, 0), cA + kstep, voffA); PG8_STAGE(PG8_SB(1, 1), cB + hstep + kstep, voffB);
;         PG8_WAIT_V(6); PG8_BAR;
.LBB0_1069:
	v_and_b32_e32 v16, 15, v195
	v_lshl_or_b32 v237, s34, 6, v16
	s_lshr_b32 s28, s35, 3
	v_and_b32_e32 v17, 48, v195
	v_lshlrev_b32_e32 v192, 6, v237
	s_movk_i32 s35, 0x3c0
	v_lshlrev_b32_e32 v19, 2, v195
	s_and_b32 s29, s91, 3
	v_and_or_b32 v18, v192, s35, v17
	s_lshl_b32 s34, s34, 13
	v_and_b32_e32 v19, 32, v19
	s_add_i32 m0, s56, 0x18000
	v_lshl_add_u64 v[6:7], v[6:7], 0, s[8:9]
	v_bitop3_b32 v18, v18, s34, v19 bitop3:0xde
	v_lshl_or_b32 v16, v16, 6, v17
	s_lshl_b32 s34, s29, 12
	global_load_lds_dwordx4 v[6:7], off
	v_lshl_add_u64 v[4:5], v[4:5], 0, s[8:9]
	s_add_i32 m0, s56, 0x1a000
	s_add_i32 s60, s56, 0x8000
	s_add_i32 s61, s56, 0xa000
	v_bitop3_b32 v142, v16, s34, v19 bitop3:0xde
	global_load_lds_dwordx4 v[4:5], off
	v_lshl_add_u64 v[2:3], v[2:3], 0, s[8:9]
	s_mov_b32 m0, s60
	s_add_u32 s34, s50, 0xb0080
	global_load_lds_dwordx4 v[2:3], off
	v_lshl_add_u64 v[0:1], v[0:1], 0, s[8:9]
	s_mov_b32 m0, s61
	s_addc_u32 s35, s51, 0
	global_load_lds_dwordx4 v[0:1], off
	s_add_i32 m0, s56, 0x1c000
	v_lshl_add_u64 v[0:1], s[34:35], 0, v[132:133]
	global_load_lds_dwordx4 v[0:1], off
	v_lshl_add_u64 v[0:1], s[34:35], 0, v[134:135]
	s_add_i32 m0, s56, 0x1e000
	s_mov_b32 s36, 0xb000
	global_load_lds_dwordx4 v[0:1], off
	s_waitcnt vmcnt(8)
	s_barrier
	v_lshrrev_b32_e32 v1, 1, v8
	v_mul_lo_u32 v0, v10, s97
	v_mad_u64_u32 v[0:1], s[34:35], v1, s36, v[0:1]
	v_or_b32_e32 v0, v0, v9
	v_add_lshl_u32 v136, v0, v11, 1
	v_lshrrev_b32_e32 v1, 1, v12
	v_mul_lo_u32 v0, v14, s97
	v_mad_u64_u32 v[0:1], s[34:35], v1, s36, v[0:1]
	s_waitcnt vmcnt(6)
	v_or_b32_e32 v0, v0, v13
	v_mov_b32_e32 v33, v32
	v_mov_b32_e32 v34, v32
	v_mov_b32_e32 v35, v32
	v_add_lshl_u32 v138, v0, v15, 1
	v_add_u32_e32 v143, 0, v18
	v_mov_b64_e32 v[0:1], v[32:33]
	v_mov_b64_e32 v[4:5], v[32:33]
	v_mov_b64_e32 v[16:17], v[32:33]
	v_mov_b64_e32 v[20:21], v[32:33]
	v_mov_b64_e32 v[38:39], v[34:35]
	v_mov_b64_e32 v[42:43], v[34:35]
	v_mov_b64_e32 v[54:55], v[34:35]
	v_mov_b64_e32 v[58:59], v[34:35]
	v_mov_b64_e32 v[8:9], v[32:33]
	v_mov_b64_e32 v[12:13], v[32:33]
	v_mov_b64_e32 v[24:25], v[32:33]
	v_mov_b64_e32 v[28:29], v[32:33]
	v_mov_b64_e32 v[46:47], v[34:35]
	v_mov_b64_e32 v[50:51], v[34:35]
	v_mov_b64_e32 v[62:63], v[34:35]
	v_mov_b64_e32 v[66:67], v[34:35]
	v_mov_b64_e32 v[70:71], v[34:35]
	v_mov_b64_e32 v[74:75], v[34:35]
	v_mov_b64_e32 v[86:87], v[34:35]
	v_mov_b64_e32 v[90:91], v[34:35]
	v_mov_b64_e32 v[102:103], v[34:35]
	v_mov_b64_e32 v[106:107], v[34:35]
	v_mov_b64_e32 v[118:119], v[34:35]
	v_mov_b64_e32 v[122:123], v[34:35]
	v_mov_b64_e32 v[78:79], v[34:35]
	v_mov_b64_e32 v[82:83], v[34:35]
	v_mov_b64_e32 v[94:95], v[34:35]
	v_mov_b64_e32 v[98:99], v[34:35]
	v_mov_b64_e32 v[110:111], v[34:35]
	v_mov_b64_e32 v[114:115], v[34:35]
	v_mov_b64_e32 v[126:127], v[34:35]
	v_mov_b64_e32 v[130:131], v[34:35]
	s_sext_i32_i8 s28, s28
	v_mov_b32_e32 v137, v32
	v_mov_b32_e32 v139, v32
	s_mov_b32 s62, 0
	v_mov_b64_e32 v[2:3], v[34:35]
	v_mov_b64_e32 v[6:7], v[34:35]
	v_mov_b64_e32 v[18:19], v[34:35]
	v_mov_b64_e32 v[22:23], v[34:35]
	v_mov_b64_e32 v[36:37], v[32:33]
	v_mov_b64_e32 v[40:41], v[32:33]
	v_mov_b64_e32 v[52:53], v[32:33]
	v_mov_b64_e32 v[56:57], v[32:33]
	v_mov_b64_e32 v[10:11], v[34:35]
	v_mov_b64_e32 v[14:15], v[34:35]
	v_mov_b64_e32 v[26:27], v[34:35]
	v_mov_b64_e32 v[30:31], v[34:35]
	v_mov_b64_e32 v[44:45], v[32:33]
	v_mov_b64_e32 v[48:49], v[32:33]
	v_mov_b64_e32 v[60:61], v[32:33]
	v_mov_b64_e32 v[64:65], v[32:33]
	v_mov_b64_e32 v[68:69], v[32:33]
	v_mov_b64_e32 v[72:73], v[32:33]
	v_mov_b64_e32 v[84:85], v[32:33]
	v_mov_b64_e32 v[88:89], v[32:33]
	v_mov_b64_e32 v[100:101], v[32:33]
	v_mov_b64_e32 v[104:105], v[32:33]
	v_mov_b64_e32 v[116:117], v[32:33]
	v_mov_b64_e32 v[120:121], v[32:33]
	v_mov_b64_e32 v[76:77], v[32:33]
	v_mov_b64_e32 v[80:81], v[32:33]
	v_mov_b64_e32 v[92:93], v[32:33]
	v_mov_b64_e32 v[96:97], v[32:33]
	v_mov_b64_e32 v[108:109], v[32:33]
	v_mov_b64_e32 v[112:113], v[32:33]
	v_mov_b64_e32 v[124:125], v[32:33]
	v_mov_b64_e32 v[128:129], v[32:33]
	s_barrier
